# ph3 row loop: after a row's operands arrive, the next row's five main cache lines are touched so the next iteration's loads hit in cache while this row's reductions and stores run; redundant counted w
# speedup vs baseline: 1.0478x; 1.0001x over previous
; #define GAS __attribute__((address_space(1)))
; DI unsigned pk2(float a, float b) { f32x2 v = {a, b}; bf2_t r = __builtin_convertvector(v, bf2_t); return __builtin_bit_cast(unsigned, r); }
; DI float bflo(unsigned w) { return __uint_as_float(w << 16); }
; DI float bfhi(unsigned w) { return __uint_as_float(w & 0xffff0000u); }
; __global__ void __launch_bounds__(256, 2) fwd_kernel(Params p) {
;     ...
;         float ss = 0.f;
; #pragma unroll
;         for (int i = 0; i < 3; ++i) { const float a = bflo(wq[i]), bq = bfhi(wq[i]); ss += a * a + bq * bq; }
;         const float rq = rsqrtf(wave_sum(ss) * (1.f / 384.f) + 1e-6f);
;         float s2 = 0.f;
; #pragma unroll
;         for (int i = 0; i < 2; ++i) { const float a = bflo(wk[i]), bq = bfhi(wk[i]); s2 += a * a + bq * bq; }
;         const float rk = rsqrtf(wave_sum(s2) * (1.f / 256.f) + 1e-6f);
; #pragma unroll
;         for (int i = 0; i < 3; ++i) *(GAS unsigned*)(pr + PE_CQ + 2 * lane + 128 * i) = pk2(bflo(wq[i]) * rq * g2q[i].x, bfhi(wq[i]) * rq * g2q[i].y);
; #pragma unroll
;         for (int i = 0; i < 2; ++i) *(GAS unsigned*)(pr + PE_CKV + 2 * lane + 128 * i) = pk2(bflo(wk[i]) * rk * g2k[i].x, bfhi(wk[i]) * rk * g2k[i].y);
;         if (lat) {
; #pragma unroll
;           for (int u = 0; u < 2; ++u) {
;             const int dp = lane + 64 * u, grp = dp >> 4, i2 = (dp & 15) * 2;
;             const float xa0 = bflo(d0[u]), xa1 = bfhi(d0[u]), xb0 = bflo(d1[u]), xb1 = bfhi(d1[u]);
;             const f32x4 c4 = cd[u];
;             *(GAS unsigned*)(pr + PE_DK + grp * 64 + i2) = pk2(xa0 * c4[0] - xb0 * c4[1], xa1 * c4[2] - xb1 * c4[3]);
;             *(GAS unsigned*)(pr + PE_DK + grp * 64 + i2 + 32) = pk2(xa0 * c4[1] + xb0 * c4[0], xa1 * c4[3] + xb1 * c4[2]);
;           }
;           if (lane < 8) {
;             const float xa0 = bflo(kr0), xa1 = bfhi(kr0), xb0 = bflo(kr1), xb1 = bfhi(kr1);
;             *(GAS unsigned*)(pr + PE_KR + 2 * lane) = pk2(xa0 * ck[0] - xb0 * ck[1], xa1 * ck[2] - xb1 * ck[3]);
;             *(GAS unsigned*)(pr + PE_KR + 2 * lane + 16) = pk2(xa0 * ck[1] + xb0 * ck[0], xa1 * ck[3] + xb1 * ck[2]);
;           }
.LBB0_167:
	s_waitcnt vmcnt(0)
	v_readlane_b32 s16, v251, 60
	v_readlane_b32 s17, v251, 61
	s_nop 3
	v_lshl_add_u64 v[236:237], v[24:25], 0, s[16:17]
	v_add_co_u32_e32 v236, vcc, 0xe960000, v236
	s_nop 1
	v_addc_co_u32_e32 v237, vcc, 0, v237, vcc
	global_load_dword v238, v[236:237], off offset:1536
	global_load_dword v239, v[236:237], off offset:1792
	global_load_dword v240, v[236:237], off offset:2048
	global_load_dword v241, v[236:237], off offset:2304
	global_load_dword v242, v[236:237], off offset:2560
	v_and_b32_e32 v57, 0xffff0000, v44
	v_and_b32_e32 v59, 0xffff0000, v42
	v_lshlrev_b32_e32 v56, 16, v44
	v_lshlrev_b32_e32 v44, 16, v43
	v_and_b32_e32 v45, 0xffff0000, v43
	v_lshlrev_b32_e32 v58, 16, v42
	v_and_b32_e32 v43, 0xffff0000, v41
	v_and_b32_e32 v61, 0xffff0000, v40
	v_mov_b32_e32 v64, v57
	v_mov_b32_e32 v65, v59
	v_lshlrev_b32_e32 v42, 16, v41
	v_lshlrev_b32_e32 v60, 16, v40
	v_mul_f32_e32 v40, v45, v45
	v_mov_b32_e32 v62, v56
	v_mov_b32_e32 v63, v58
	v_pk_mul_f32 v[64:65], v[64:65], v[64:65]
	v_mov_b32_e32 v66, v43
	v_mov_b32_e32 v67, v61
	v_pk_fma_f32 v[40:41], v[44:45], v[44:45], v[40:41] op_sel_hi:[1,1,0]
	v_pk_fma_f32 v[62:63], v[62:63], v[62:63], v[64:65]
	v_mov_b32_e32 v64, v42
	v_mov_b32_e32 v65, v60
	v_pk_mul_f32 v[66:67], v[66:67], v[66:67]
	v_pk_add_f32 v[40:41], v[62:63], v[40:41]
	v_pk_fma_f32 v[64:65], v[64:65], v[64:65], v[66:67]
	v_mov_b32_e32 v67, v40
	v_mov_b32_e32 v66, v64
	v_mov_b32_e32 v62, v65
	v_pk_add_f32 v[40:41], v[66:67], v[62:63]
	ds_bpermute_b32 v63, v32, v41
	ds_bpermute_b32 v62, v32, v40
	s_mov_b64 s[10:11], 0xe960600
	v_lshl_add_u64 v[64:65], v[24:25], 0, s[10:11]
	s_mov_b32 s10, 0x3b800000
	s_mov_b32 s11, 0x3b2aaaab
	s_waitcnt lgkmcnt(0)
	v_pk_add_f32 v[40:41], v[40:41], v[62:63]
	ds_bpermute_b32 v63, v33, v41
	ds_bpermute_b32 v62, v33, v40
	s_mov_b64 s[16:17], 0xe960700
	v_lshl_add_u64 v[66:67], v[24:25], 0, s[16:17]
	s_mov_b64 s[16:17], 0xe960800
	v_lshl_add_u64 v[68:69], v[24:25], 0, s[16:17]
	s_waitcnt lgkmcnt(0)
	v_pk_add_f32 v[40:41], v[40:41], v[62:63]
	ds_bpermute_b32 v63, v34, v41
	ds_bpermute_b32 v62, v34, v40
	s_mov_b64 s[16:17], 0xe960900
	s_waitcnt lgkmcnt(0)
	v_pk_add_f32 v[40:41], v[40:41], v[62:63]
	ds_bpermute_b32 v63, v35, v41
	ds_bpermute_b32 v62, v35, v40
	s_waitcnt lgkmcnt(0)
	v_pk_add_f32 v[40:41], v[40:41], v[62:63]
	ds_bpermute_b32 v63, v36, v41
	ds_bpermute_b32 v62, v36, v40
	s_waitcnt lgkmcnt(0)
	v_pk_add_f32 v[40:41], v[40:41], v[62:63]
	ds_bpermute_b32 v63, v37, v41
	ds_bpermute_b32 v62, v37, v40
	s_waitcnt lgkmcnt(0)
	v_pk_add_f32 v[40:41], v[40:41], v[62:63]
	s_nop 0
	v_pk_fma_f32 v[40:41], v[40:41], s[10:11], v[186:187] op_sel_hi:[1,1,0]
	s_mov_b32 s10, 0x800000
	v_mul_f32_e32 v62, 0x4b800000, v41
	v_mul_f32_e32 v63, 0x4b800000, v40
	v_cmp_gt_f32_e32 vcc, s10, v41
	v_cmp_gt_f32_e64 s[42:43], s10, v40
	s_mov_b64 s[10:11], 0xe960a00
	v_cndmask_b32_e32 v41, v41, v62, vcc
	v_cndmask_b32_e64 v40, v40, v63, s[42:43]
	v_rsq_f32_e32 v70, v41
	v_rsq_f32_e32 v71, v40
	v_lshl_add_u64 v[40:41], v[24:25], 0, s[16:17]
	v_lshl_add_u64 v[62:63], v[24:25], 0, s[10:11]
	v_mul_f32_e32 v72, 0x45800000, v70
	v_mul_f32_e32 v73, 0x45800000, v71
	v_cndmask_b32_e32 v70, v70, v72, vcc
	v_cndmask_b32_e64 v72, v71, v73, s[42:43]
	v_pk_mul_f32 v[56:57], v[70:71], v[56:57] op_sel_hi:[0,1]
	v_pk_mul_f32 v[42:43], v[72:73], v[42:43] op_sel_hi:[0,1]
	v_pk_mul_f32 v[44:45], v[70:71], v[44:45] op_sel_hi:[0,1]
	v_pk_mul_f32 v[58:59], v[70:71], v[58:59] op_sel_hi:[0,1]
	v_pk_mul_f32 v[46:47], v[226:227], v[56:57]
	v_pk_mul_f32 v[42:43], v[232:233], v[42:43]
	v_pk_mul_f32 v[44:45], v[228:229], v[44:45]
	v_pk_mul_f32 v[48:49], v[230:231], v[58:59]
	v_cvt_pk_bf16_f32 v46, v46, v47
	v_cvt_pk_bf16_f32 v42, v42, v43
	v_cvt_pk_bf16_f32 v44, v44, v45
	v_cvt_pk_bf16_f32 v45, v48, v49
	global_store_dword v[64:65], v46, off
	global_store_dword v[66:67], v44, off
	global_store_dword v[68:69], v45, off
	global_store_dword v[40:41], v42, off
	v_pk_mul_f32 v[40:41], v[72:73], v[60:61] op_sel_hi:[0,1]
	v_pk_mul_f32 v[40:41], v[234:235], v[40:41]
	s_andn2_b64 vcc, exec, s[14:15]
	v_cvt_pk_bf16_f32 v40, v40, v41
	global_store_dword v[62:63], v40, off
	s_cbranch_vccnz .LBB0_161
	v_lshlrev_b32_e32 v42, 16, v28
	v_and_b32_e32 v43, 0xffff0000, v28
	v_mov_b32_e32 v46, v3
	v_mov_b32_e32 v47, v5
	v_lshlrev_b32_e32 v40, 16, v30
	v_and_b32_e32 v41, 0xffff0000, v30
	v_mov_b32_e32 v44, v2
	v_mov_b32_e32 v45, v4
	v_pk_mul_f32 v[48:49], v[46:47], v[42:43]
	s_mov_b32 s10, 0xe960000
	v_pk_fma_f32 v[48:49], v[44:45], v[40:41], v[48:49] neg_lo:[0,0,1] neg_hi:[0,0,1]
	v_pk_mul_f32 v[42:43], v[44:45], v[42:43]
	v_cvt_pk_bf16_f32 v50, v48, v49
	v_add_co_u32_e32 v48, vcc, s10, v26
	v_pk_fma_f32 v[40:41], v[46:47], v[40:41], v[42:43]
	s_nop 0
	v_addc_co_u32_e32 v49, vcc, 0, v27, vcc
	v_cvt_pk_bf16_f32 v40, v40, v41
	v_lshlrev_b32_e32 v42, 16, v29
	v_and_b32_e32 v43, 0xffff0000, v29
	v_mov_b32_e32 v44, v6
	v_mov_b32_e32 v45, v8
	v_mov_b32_e32 v46, v7
	v_mov_b32_e32 v47, v9
	global_store_dword v[48:49], v50, off offset:3840
	global_store_dword v[48:49], v40, off offset:3904
	v_lshlrev_b32_e32 v40, 16, v31
	v_and_b32_e32 v41, 0xffff0000, v31
	v_pk_mul_f32 v[48:49], v[46:47], v[42:43]
	v_pk_mul_f32 v[42:43], v[44:45], v[42:43]
	v_pk_fma_f32 v[48:49], v[44:45], v[40:41], v[48:49] neg_lo:[0,0,1] neg_hi:[0,0,1]
	v_add_co_u32_e32 v26, vcc, 0xe961000, v26
	v_pk_fma_f32 v[40:41], v[46:47], v[40:41], v[42:43]
	v_cvt_pk_bf16_f32 v48, v48, v49
	v_addc_co_u32_e32 v27, vcc, 0, v27, vcc
	v_cvt_pk_bf16_f32 v40, v40, v41
	global_store_dword v[26:27], v48, off offset:256
	global_store_dword v[26:27], v40, off offset:320
	s_and_saveexec_b64 s[14:15], s[40:41]
	s_cbranch_execz .LBB0_160
	v_lshlrev_b32_e32 v26, 16, v39
	v_and_b32_e32 v27, 0xffff0000, v39
	v_lshlrev_b32_e32 v40, 16, v38
	v_and_b32_e32 v41, 0xffff0000, v38
	v_mov_b32_e32 v39, v12
	v_mov_b32_e32 v12, v11
	v_mov_b32_e32 v38, v10
	v_pk_mul_f32 v[10:11], v[12:13], v[40:41]
	v_pk_mul_f32 v[12:13], v[12:13], v[26:27]
	v_pk_fma_f32 v[10:11], v[38:39], v[26:27], v[10:11] neg_lo:[0,0,1] neg_hi:[0,0,1]
	v_pk_fma_f32 v[12:13], v[38:39], v[40:41], v[12:13]
	v_cvt_pk_bf16_f32 v42, v10, v11
	v_add_co_u32_e32 v10, vcc, 0xe961000, v24
	v_cvt_pk_bf16_f32 v12, v12, v13
	s_nop 0
	v_addc_co_u32_e32 v11, vcc, 0, v25, vcc
	global_store_dword v[10:11], v42, off offset:1792
	global_store_dword v[10:11], v12, off offset:1824
	s_branch .LBB0_160
